# up-GEMM row-scale table loads merged per unit; nt on touch-once residual (x) loads of the first residual GEMM epilogue and on conv-phase row loads
# speedup vs baseline: 1.0191x; 1.0038x over previous
.LBB0_360:
	v_add_u32_e32 v24, -7, v130
	v_ashrrev_i32_e32 v25, 31, v24
	v_lshlrev_b64 v[24:25], 12, v[24:25]
	v_lshl_add_u64 v[26:27], v[120:121], 0, v[24:25]
	v_lshl_add_u64 v[148:149], v[122:123], 0, v[24:25]
	v_add_u32_e32 v24, -6, v130
	v_ashrrev_i32_e32 v25, 31, v24
	v_lshlrev_b64 v[24:25], 12, v[24:25]
	v_lshl_add_u64 v[28:29], v[120:121], 0, v[24:25]
	v_lshl_add_u64 v[146:147], v[122:123], 0, v[24:25]
	v_add_u32_e32 v24, -5, v130
	v_ashrrev_i32_e32 v25, 31, v24
	v_lshlrev_b64 v[24:25], 12, v[24:25]
	global_load_dwordx4 v[84:87], v[26:27], off nt
	global_load_dwordx4 v[76:79], v[28:29], off nt
	v_lshl_add_u64 v[26:27], v[120:121], 0, v[24:25]
	v_lshl_add_u64 v[144:145], v[122:123], 0, v[24:25]
	v_add_u32_e32 v24, -4, v130
	v_ashrrev_i32_e32 v25, 31, v24
	v_lshlrev_b64 v[24:25], 12, v[24:25]
	v_lshl_add_u64 v[28:29], v[120:121], 0, v[24:25]
	v_lshl_add_u64 v[142:143], v[122:123], 0, v[24:25]
	v_add_u32_e32 v24, -3, v130
	v_ashrrev_i32_e32 v25, 31, v24
	v_lshlrev_b64 v[24:25], 12, v[24:25]
	global_load_dwordx4 v[80:83], v[148:149], off nt
	global_load_dwordx4 v[72:75], v[146:147], off nt
	global_load_dwordx4 v[68:71], v[26:27], off nt
	global_load_dwordx4 v[60:63], v[28:29], off nt
	v_lshl_add_u64 v[26:27], v[120:121], 0, v[24:25]
	v_lshl_add_u64 v[140:141], v[122:123], 0, v[24:25]
	v_add_u32_e32 v24, -2, v130
	v_ashrrev_i32_e32 v25, 31, v24
	v_lshlrev_b64 v[24:25], 12, v[24:25]
	v_lshl_add_u64 v[28:29], v[120:121], 0, v[24:25]
	v_lshl_add_u64 v[138:139], v[122:123], 0, v[24:25]
	v_add_u32_e32 v24, -1, v130
	v_ashrrev_i32_e32 v25, 31, v24
	v_lshlrev_b64 v[24:25], 12, v[24:25]
	v_ashrrev_i32_e32 v131, 31, v130
	global_load_dwordx4 v[64:67], v[144:145], off nt
	global_load_dwordx4 v[56:59], v[142:143], off nt
	global_load_dwordx4 v[52:55], v[26:27], off nt
	global_load_dwordx4 v[44:47], v[28:29], off nt
	v_lshl_add_u64 v[26:27], v[120:121], 0, v[24:25]
	v_lshl_add_u64 v[136:137], v[122:123], 0, v[24:25]
	v_lshlrev_b64 v[24:25], 12, v[130:131]
	v_lshl_add_u64 v[28:29], v[120:121], 0, v[24:25]
	global_load_dwordx4 v[48:51], v[140:141], off nt
	global_load_dwordx4 v[40:43], v[138:139], off nt
	global_load_dwordx4 v[36:39], v[26:27], off nt
	s_nop 0
	global_load_dwordx4 v[28:31], v[28:29], off nt
	v_lshl_add_u64 v[134:135], v[122:123], 0, v[24:25]
	global_load_dwordx4 v[32:35], v[136:137], off nt
	global_load_dwordx4 v[24:27], v[134:135], off nt
	v_mul_hi_i32 v88, v150, s96
	v_lshrrev_b32_e32 v89, 31, v88
	v_ashrrev_i32_e32 v88, 4, v88
	v_add_u32_e32 v132, v88, v89
	s_movk_i32 s6, 0xf7f0
	v_mad_i32_i24 v131, v132, s6, v130
	s_movk_i32 s6, 0x407
	v_cmp_lt_i32_e64 s[8:9], s6, v150
	s_movk_i32 s6, 0x408
	v_cmp_gt_i32_e64 s[6:7], s6, v150
	s_and_saveexec_b64 s[16:17], s[6:7]
	s_xor_b64 s[16:17], exec, s[16:17]
	s_cbranch_execz .LBB0_364
	v_cmp_ne_u32_e32 vcc, 7, v131
	v_mov_b32_e32 v107, 0
	v_mov_b32_e32 v106, 0
	v_mov_b32_e32 v105, 0
	v_mov_b32_e32 v104, 0
	v_mov_b32_e32 v115, 0
	v_mov_b32_e32 v114, 0
	v_mov_b32_e32 v113, 0
	v_mov_b32_e32 v112, 0
	v_mov_b32_e32 v111, 0
	v_mov_b32_e32 v110, 0
	v_mov_b32_e32 v109, 0
	v_mov_b32_e32 v108, 0
	v_mov_b32_e32 v119, 0
	v_mov_b32_e32 v118, 0
	v_mov_b32_e32 v117, 0
	v_mov_b32_e32 v116, 0
	s_and_saveexec_b64 s[18:19], vcc
	s_cbranch_execz .LBB0_363
	v_add_u32_e32 v88, -9, v130
	v_add_u32_e32 v92, -8, v130
	v_ashrrev_i32_e32 v89, 31, v88
	v_ashrrev_i32_e32 v93, 31, v92
	v_lshlrev_b64 v[88:89], 12, v[88:89]
	v_lshlrev_b64 v[92:93], 12, v[92:93]
	v_lshl_add_u64 v[88:89], v[120:121], 0, v[88:89]
	v_lshl_add_u64 v[92:93], v[120:121], 0, v[92:93]
	global_load_dwordx4 v[88:91], v[88:89], off nt
	s_nop 0
	global_load_dwordx4 v[92:95], v[92:93], off nt
	s_waitcnt vmcnt(1)
	v_lshlrev_b32_e32 v116, 16, v88
	v_and_b32_e32 v117, 0xffff0000, v88
	v_lshlrev_b32_e32 v118, 16, v89
	v_and_b32_e32 v119, 0xffff0000, v89
	v_lshlrev_b32_e32 v108, 16, v90
	v_and_b32_e32 v109, 0xffff0000, v90
	v_lshlrev_b32_e32 v110, 16, v91
	v_and_b32_e32 v111, 0xffff0000, v91
	s_waitcnt vmcnt(0)
	v_lshlrev_b32_e32 v112, 16, v92
	v_and_b32_e32 v113, 0xffff0000, v92
	v_lshlrev_b32_e32 v114, 16, v93
	v_and_b32_e32 v115, 0xffff0000, v93
	v_lshlrev_b32_e32 v104, 16, v94
	v_and_b32_e32 v105, 0xffff0000, v94
	v_lshlrev_b32_e32 v106, 16, v95
	v_and_b32_e32 v107, 0xffff0000, v95

.LBB0_364:
	s_or_saveexec_b64 s[16:17], s[16:17]
	v_add_u32_e32 v88, 0xffffdfb9, v130
	v_lshrrev_b32_e32 v192, 1, v88
	v_mov_b32_e32 v88, 0
	v_mov_b32_e32 v89, 0
	v_mov_b32_e32 v90, 0
	v_mov_b32_e32 v91, 0
	v_mov_b32_e32 v92, 0
	v_mov_b32_e32 v93, 0
	v_mov_b32_e32 v94, 0
	v_mov_b32_e32 v95, 0
	v_mov_b32_e32 v96, 0
	v_mov_b32_e32 v97, 0
	v_mov_b32_e32 v98, 0
	v_mov_b32_e32 v99, 0
	v_mov_b32_e32 v100, 0
	v_mov_b32_e32 v101, 0
	v_mov_b32_e32 v102, 0
	v_mov_b32_e32 v103, 0
	s_xor_b64 exec, exec, s[16:17]
	s_cbranch_execz .LBB0_366
	v_lshlrev_b64 v[88:89], 13, v[192:193]
	v_lshl_add_u64 v[88:89], v[124:125], 0, v[88:89]
	s_mov_b64 s[18:19], 0x2000
	v_lshl_add_u64 v[90:91], v[88:89], 0, s[18:19]
	s_mov_b64 s[18:19], 0x4000
	v_lshl_add_u64 v[92:93], v[88:89], 0, s[18:19]
	s_mov_b64 s[18:19], 0x6000
	v_lshl_add_u64 v[100:101], v[88:89], 0, s[18:19]
	s_movk_i32 s18, 0x2000
	v_add_co_u32_e32 v102, vcc, s18, v88
	s_movk_i32 s18, 0x4000
	s_nop 0
	v_addc_co_u32_e32 v103, vcc, 0, v89, vcc
	v_add_co_u32_e32 v96, vcc, s18, v88
	global_load_dwordx4 v[116:119], v[88:89], off nt
	global_load_dwordx4 v[108:111], v[88:89], off offset:16 nt
	v_addc_co_u32_e32 v97, vcc, 0, v89, vcc
	v_add_co_u32_e32 v98, vcc, 0x6000, v88
	global_load_dwordx4 v[104:107], v[90:91], off offset:16 nt
	s_nop 0
	global_load_dwordx4 v[92:95], v[92:93], off offset:16 nt
	v_addc_co_u32_e32 v99, vcc, 0, v89, vcc
	global_load_dwordx4 v[88:91], v[96:97], off nt
	s_nop 0
	global_load_dwordx4 v[96:99], v[98:99], off nt
	s_nop 0
	global_load_dwordx4 v[112:115], v[102:103], off nt
	s_nop 0
	global_load_dwordx4 v[100:103], v[100:101], off offset:16 nt

.LBB0_425:
	v_lshl_add_u32 v6, s80, 8, v4
	v_ashrrev_i32_e32 v7, 31, v6
	v_lshlrev_b64 v[6:7], 8, v[6:7]
	v_lshl_add_u64 v[22:23], v[0:1], 0, v[6:7]
	global_load_dwordx4 v[6:9], v[22:23], off offset:48
	global_load_dwordx4 v[10:13], v[22:23], off offset:32
	global_load_dwordx4 v[14:17], v[22:23], off offset:16
	global_load_dwordx4 v[18:21], v[22:23], off
	global_load_dwordx4 v[40:43], v[22:23], off offset:112
	global_load_dwordx4 v[44:47], v[22:23], off offset:96
	global_load_dwordx4 v[48:51], v[22:23], off offset:80
	global_load_dwordx4 v[52:55], v[22:23], off offset:64
	s_waitcnt vmcnt(7)
	v_add_f32_e32 v6, v6, v7
	s_waitcnt vmcnt(6)
	v_add_f32_e32 v10, v10, v11
	s_waitcnt vmcnt(5)
	v_add_f32_e32 v14, v14, v15
	s_waitcnt vmcnt(4)
	v_add_f32_e32 v5, v18, v19
	v_add_f32_e32 v18, v20, v21
	v_add_f32_e32 v5, v5, v18
	v_add_f32_e32 v15, v16, v17
	v_add_f32_e32 v5, 0, v5
	v_add_f32_e32 v14, v14, v15
	v_add_f32_e32 v11, v12, v13
	v_add_f32_e32 v5, v5, v14
	v_add_f32_e32 v10, v10, v11
	v_add_f32_e32 v7, v8, v9
	v_add_f32_e32 v5, v5, v10
	v_add_f32_e32 v6, v6, v7
	v_add_f32_e32 v5, v5, v6
	s_waitcnt vmcnt(3)
	v_add_f32_e32 v40, v40, v41
	s_waitcnt vmcnt(2)
	v_add_f32_e32 v44, v44, v45
	s_waitcnt vmcnt(1)
	v_add_f32_e32 v48, v48, v49
	s_waitcnt vmcnt(0)
	v_add_f32_e32 v52, v52, v53
	v_add_f32_e32 v53, v54, v55
	v_add_f32_e32 v52, v52, v53
	v_add_f32_e32 v49, v50, v51
	v_add_f32_e32 v5, v5, v52
	v_add_f32_e32 v48, v48, v49
	v_add_f32_e32 v45, v46, v47
	v_add_f32_e32 v5, v5, v48
	v_add_f32_e32 v44, v44, v45
	v_add_f32_e32 v41, v42, v43
	v_add_f32_e32 v5, v5, v44
	v_add_f32_e32 v40, v40, v41
	v_add_f32_e32 v5, v5, v40
	ds_bpermute_b32 v6, v3, v5
	s_and_saveexec_b64 s[18:19], s[6:7]
	s_cbranch_execz .LBB0_427
	s_waitcnt lgkmcnt(0)
	v_add_f32_e32 v5, v5, v6
	v_fmamk_f32 v5, v5, 0x3a000000, v223
	v_mul_f32_e32 v6, 0x4b800000, v5
	v_cmp_gt_f32_e32 vcc, s56, v5
	s_nop 1
	v_cndmask_b32_e32 v5, v5, v6, vcc
	v_rsq_f32_e32 v5, v5
	s_nop 0
	v_mul_f32_e32 v6, 0x45800000, v5
	v_cndmask_b32_e32 v5, v5, v6, vcc
	ds_write_b32 v2, v5 offset:1024

.LBB0_436:
	v_lshl_add_u32 v6, s80, 8, v4
	v_ashrrev_i32_e32 v7, 31, v6
	v_lshlrev_b64 v[6:7], 8, v[6:7]
	v_lshl_add_u64 v[22:23], v[0:1], 0, v[6:7]
	global_load_dwordx4 v[6:9], v[22:23], off offset:48
	global_load_dwordx4 v[10:13], v[22:23], off offset:32
	global_load_dwordx4 v[14:17], v[22:23], off offset:16
	global_load_dwordx4 v[18:21], v[22:23], off
	global_load_dwordx4 v[40:43], v[22:23], off offset:112
	global_load_dwordx4 v[44:47], v[22:23], off offset:96
	global_load_dwordx4 v[48:51], v[22:23], off offset:80
	global_load_dwordx4 v[52:55], v[22:23], off offset:64
	s_waitcnt vmcnt(7)
	v_add_f32_e32 v6, v6, v7
	s_waitcnt vmcnt(6)
	v_add_f32_e32 v10, v10, v11
	s_waitcnt vmcnt(5)
	v_add_f32_e32 v14, v14, v15
	s_waitcnt vmcnt(4)
	v_add_f32_e32 v5, v18, v19
	v_add_f32_e32 v18, v20, v21
	v_add_f32_e32 v5, v5, v18
	v_add_f32_e32 v15, v16, v17
	v_add_f32_e32 v5, 0, v5
	v_add_f32_e32 v14, v14, v15
	v_add_f32_e32 v11, v12, v13
	v_add_f32_e32 v5, v5, v14
	v_add_f32_e32 v10, v10, v11
	v_add_f32_e32 v7, v8, v9
	v_add_f32_e32 v5, v5, v10
	v_add_f32_e32 v6, v6, v7
	v_add_f32_e32 v5, v5, v6
	s_waitcnt vmcnt(3)
	v_add_f32_e32 v40, v40, v41
	s_waitcnt vmcnt(2)
	v_add_f32_e32 v44, v44, v45
	s_waitcnt vmcnt(1)
	v_add_f32_e32 v48, v48, v49
	s_waitcnt vmcnt(0)
	v_add_f32_e32 v52, v52, v53
	v_add_f32_e32 v53, v54, v55
	v_add_f32_e32 v52, v52, v53
	v_add_f32_e32 v49, v50, v51
	v_add_f32_e32 v5, v5, v52
	v_add_f32_e32 v48, v48, v49
	v_add_f32_e32 v45, v46, v47
	v_add_f32_e32 v5, v5, v48
	v_add_f32_e32 v44, v44, v45
	v_add_f32_e32 v41, v42, v43
	v_add_f32_e32 v5, v5, v44
	v_add_f32_e32 v40, v40, v41
	v_add_f32_e32 v5, v5, v40
	ds_bpermute_b32 v6, v3, v5
	s_and_saveexec_b64 s[18:19], s[6:7]
	s_cbranch_execz .LBB0_438
	s_waitcnt lgkmcnt(0)
	v_add_f32_e32 v5, v5, v6
	v_fmamk_f32 v5, v5, 0x3a000000, v223
	v_mul_f32_e32 v6, 0x4b800000, v5
	v_cmp_gt_f32_e32 vcc, s56, v5
	s_nop 1
	v_cndmask_b32_e32 v5, v5, v6, vcc
	v_rsq_f32_e32 v5, v5
	s_nop 0
	v_mul_f32_e32 v6, 0x45800000, v5
	v_cndmask_b32_e32 v5, v5, v6, vcc
	ds_write_b32 v2, v5 offset:2048

.LBB0_447:
	v_lshl_add_u32 v6, s80, 8, v4
	v_ashrrev_i32_e32 v7, 31, v6
	v_lshlrev_b64 v[6:7], 8, v[6:7]
	v_lshl_add_u64 v[22:23], v[0:1], 0, v[6:7]
	global_load_dwordx4 v[6:9], v[22:23], off offset:48
	global_load_dwordx4 v[10:13], v[22:23], off offset:32
	global_load_dwordx4 v[14:17], v[22:23], off offset:16
	global_load_dwordx4 v[18:21], v[22:23], off
	global_load_dwordx4 v[40:43], v[22:23], off offset:112
	global_load_dwordx4 v[44:47], v[22:23], off offset:96
	global_load_dwordx4 v[48:51], v[22:23], off offset:80
	global_load_dwordx4 v[52:55], v[22:23], off offset:64
	s_waitcnt vmcnt(7)
	v_add_f32_e32 v6, v6, v7
	s_waitcnt vmcnt(6)
	v_add_f32_e32 v10, v10, v11
	s_waitcnt vmcnt(5)
	v_add_f32_e32 v14, v14, v15
	s_waitcnt vmcnt(4)
	v_add_f32_e32 v5, v18, v19
	v_add_f32_e32 v18, v20, v21
	v_add_f32_e32 v5, v5, v18
	v_add_f32_e32 v15, v16, v17
	v_add_f32_e32 v5, 0, v5
	v_add_f32_e32 v14, v14, v15
	v_add_f32_e32 v11, v12, v13
	v_add_f32_e32 v5, v5, v14
	v_add_f32_e32 v10, v10, v11
	v_add_f32_e32 v7, v8, v9
	v_add_f32_e32 v5, v5, v10
	v_add_f32_e32 v6, v6, v7
	v_add_f32_e32 v5, v5, v6
	s_waitcnt vmcnt(3)
	v_add_f32_e32 v40, v40, v41
	s_waitcnt vmcnt(2)
	v_add_f32_e32 v44, v44, v45
	s_waitcnt vmcnt(1)
	v_add_f32_e32 v48, v48, v49
	s_waitcnt vmcnt(0)
	v_add_f32_e32 v52, v52, v53
	v_add_f32_e32 v53, v54, v55
	v_add_f32_e32 v52, v52, v53
	v_add_f32_e32 v49, v50, v51
	v_add_f32_e32 v5, v5, v52
	v_add_f32_e32 v48, v48, v49
	v_add_f32_e32 v45, v46, v47
	v_add_f32_e32 v5, v5, v48
	v_add_f32_e32 v44, v44, v45
	v_add_f32_e32 v41, v42, v43
	v_add_f32_e32 v5, v5, v44
	v_add_f32_e32 v40, v40, v41
	v_add_f32_e32 v5, v5, v40
	ds_bpermute_b32 v6, v3, v5
	s_and_saveexec_b64 s[18:19], s[6:7]
	s_cbranch_execz .LBB0_449
	s_waitcnt lgkmcnt(0)
	v_add_f32_e32 v5, v5, v6
	v_fmamk_f32 v5, v5, 0x3a000000, v223
	v_mul_f32_e32 v6, 0x4b800000, v5
	v_cmp_gt_f32_e32 vcc, s56, v5
	s_nop 1
	v_cndmask_b32_e32 v5, v5, v6, vcc
	v_rsq_f32_e32 v5, v5
	s_nop 0
	v_mul_f32_e32 v6, 0x45800000, v5
	v_cndmask_b32_e32 v5, v5, v6, vcc
	ds_write_b32 v2, v5 offset:3072

.LBB0_458:
	v_lshl_add_u32 v6, s80, 8, v4
	v_ashrrev_i32_e32 v7, 31, v6
	v_lshlrev_b64 v[6:7], 8, v[6:7]
	v_lshl_add_u64 v[22:23], v[0:1], 0, v[6:7]
	global_load_dwordx4 v[6:9], v[22:23], off offset:48
	global_load_dwordx4 v[10:13], v[22:23], off offset:32
	global_load_dwordx4 v[14:17], v[22:23], off offset:16
	global_load_dwordx4 v[18:21], v[22:23], off
	global_load_dwordx4 v[40:43], v[22:23], off offset:112
	global_load_dwordx4 v[44:47], v[22:23], off offset:96
	global_load_dwordx4 v[48:51], v[22:23], off offset:80
	global_load_dwordx4 v[52:55], v[22:23], off offset:64
	s_waitcnt vmcnt(7)
	v_add_f32_e32 v6, v6, v7
	s_waitcnt vmcnt(6)
	v_add_f32_e32 v10, v10, v11
	s_waitcnt vmcnt(5)
	v_add_f32_e32 v14, v14, v15
	s_waitcnt vmcnt(4)
	v_add_f32_e32 v5, v18, v19
	v_add_f32_e32 v18, v20, v21
	v_add_f32_e32 v5, v5, v18
	v_add_f32_e32 v15, v16, v17
	v_add_f32_e32 v5, 0, v5
	v_add_f32_e32 v14, v14, v15
	v_add_f32_e32 v11, v12, v13
	v_add_f32_e32 v5, v5, v14
	v_add_f32_e32 v10, v10, v11
	v_add_f32_e32 v7, v8, v9
	v_add_f32_e32 v5, v5, v10
	v_add_f32_e32 v6, v6, v7
	v_add_f32_e32 v5, v5, v6
	s_waitcnt vmcnt(3)
	v_add_f32_e32 v40, v40, v41
	s_waitcnt vmcnt(2)
	v_add_f32_e32 v44, v44, v45
	s_waitcnt vmcnt(1)
	v_add_f32_e32 v48, v48, v49
	s_waitcnt vmcnt(0)
	v_add_f32_e32 v52, v52, v53
	v_add_f32_e32 v53, v54, v55
	v_add_f32_e32 v52, v52, v53
	v_add_f32_e32 v49, v50, v51
	v_add_f32_e32 v5, v5, v52
	v_add_f32_e32 v48, v48, v49
	v_add_f32_e32 v45, v46, v47
	v_add_f32_e32 v5, v5, v48
	v_add_f32_e32 v44, v44, v45
	v_add_f32_e32 v41, v42, v43
	v_add_f32_e32 v5, v5, v44
	v_add_f32_e32 v40, v40, v41
	v_add_f32_e32 v5, v5, v40
	ds_bpermute_b32 v6, v3, v5
	s_and_saveexec_b64 s[18:19], s[6:7]
	s_cbranch_execz .LBB0_460
	s_waitcnt lgkmcnt(0)
	v_add_f32_e32 v5, v5, v6
	v_fmamk_f32 v5, v5, 0x3a000000, v223
	v_mul_f32_e32 v6, 0x4b800000, v5
	v_cmp_gt_f32_e32 vcc, s56, v5
	s_nop 1
	v_cndmask_b32_e32 v5, v5, v6, vcc
	v_rsq_f32_e32 v5, v5
	s_nop 0
	v_mul_f32_e32 v6, 0x45800000, v5
	v_cndmask_b32_e32 v5, v5, v6, vcc
	ds_write_b32 v2, v5 offset:4096

.LBB0_469:
	v_lshl_add_u32 v6, s80, 8, v4
	v_ashrrev_i32_e32 v7, 31, v6
	v_lshlrev_b64 v[6:7], 8, v[6:7]
	v_lshl_add_u64 v[22:23], v[0:1], 0, v[6:7]
	global_load_dwordx4 v[6:9], v[22:23], off offset:48
	global_load_dwordx4 v[10:13], v[22:23], off offset:32
	global_load_dwordx4 v[14:17], v[22:23], off offset:16
	global_load_dwordx4 v[18:21], v[22:23], off
	global_load_dwordx4 v[40:43], v[22:23], off offset:112
	global_load_dwordx4 v[44:47], v[22:23], off offset:96
	global_load_dwordx4 v[48:51], v[22:23], off offset:80
	global_load_dwordx4 v[52:55], v[22:23], off offset:64
	s_waitcnt vmcnt(7)
	v_add_f32_e32 v6, v6, v7
	s_waitcnt vmcnt(6)
	v_add_f32_e32 v10, v10, v11
	s_waitcnt vmcnt(5)
	v_add_f32_e32 v14, v14, v15
	s_waitcnt vmcnt(4)
	v_add_f32_e32 v5, v18, v19
	v_add_f32_e32 v18, v20, v21
	v_add_f32_e32 v5, v5, v18
	v_add_f32_e32 v15, v16, v17
	v_add_f32_e32 v5, 0, v5
	v_add_f32_e32 v14, v14, v15
	v_add_f32_e32 v11, v12, v13
	v_add_f32_e32 v5, v5, v14
	v_add_f32_e32 v10, v10, v11
	v_add_f32_e32 v7, v8, v9
	v_add_f32_e32 v5, v5, v10
	v_add_f32_e32 v6, v6, v7
	v_add_f32_e32 v5, v5, v6
	s_waitcnt vmcnt(3)
	v_add_f32_e32 v40, v40, v41
	s_waitcnt vmcnt(2)
	v_add_f32_e32 v44, v44, v45
	s_waitcnt vmcnt(1)
	v_add_f32_e32 v48, v48, v49
	s_waitcnt vmcnt(0)
	v_add_f32_e32 v52, v52, v53
	v_add_f32_e32 v53, v54, v55
	v_add_f32_e32 v52, v52, v53
	v_add_f32_e32 v49, v50, v51
	v_add_f32_e32 v5, v5, v52
	v_add_f32_e32 v48, v48, v49
	v_add_f32_e32 v45, v46, v47
	v_add_f32_e32 v5, v5, v48
	v_add_f32_e32 v44, v44, v45
	v_add_f32_e32 v41, v42, v43
	v_add_f32_e32 v5, v5, v44
	v_add_f32_e32 v40, v40, v41
	v_add_f32_e32 v5, v5, v40
	ds_bpermute_b32 v6, v3, v5
	s_and_saveexec_b64 s[18:19], s[6:7]
	s_cbranch_execz .LBB0_471
	s_waitcnt lgkmcnt(0)
	v_add_f32_e32 v5, v5, v6
	v_fmamk_f32 v5, v5, 0x3a000000, v223
	v_mul_f32_e32 v6, 0x4b800000, v5
	v_cmp_gt_f32_e32 vcc, s56, v5
	s_nop 1
	v_cndmask_b32_e32 v5, v5, v6, vcc
	v_rsq_f32_e32 v5, v5
	s_nop 0
	v_mul_f32_e32 v6, 0x45800000, v5
	v_cndmask_b32_e32 v5, v5, v6, vcc
	ds_write_b32 v2, v5 offset:5120

.LBB0_480:
	v_lshl_add_u32 v6, s80, 8, v4
	v_ashrrev_i32_e32 v7, 31, v6
	v_lshlrev_b64 v[6:7], 8, v[6:7]
	v_lshl_add_u64 v[22:23], v[0:1], 0, v[6:7]
	global_load_dwordx4 v[6:9], v[22:23], off offset:48
	global_load_dwordx4 v[10:13], v[22:23], off offset:32
	global_load_dwordx4 v[14:17], v[22:23], off offset:16
	global_load_dwordx4 v[18:21], v[22:23], off
	global_load_dwordx4 v[40:43], v[22:23], off offset:112
	global_load_dwordx4 v[44:47], v[22:23], off offset:96
	global_load_dwordx4 v[48:51], v[22:23], off offset:80
	global_load_dwordx4 v[52:55], v[22:23], off offset:64
	s_waitcnt vmcnt(7)
	v_add_f32_e32 v6, v6, v7
	s_waitcnt vmcnt(6)
	v_add_f32_e32 v10, v10, v11
	s_waitcnt vmcnt(5)
	v_add_f32_e32 v14, v14, v15
	s_waitcnt vmcnt(4)
	v_add_f32_e32 v5, v18, v19
	v_add_f32_e32 v18, v20, v21
	v_add_f32_e32 v5, v5, v18
	v_add_f32_e32 v15, v16, v17
	v_add_f32_e32 v5, 0, v5
	v_add_f32_e32 v14, v14, v15
	v_add_f32_e32 v11, v12, v13
	v_add_f32_e32 v5, v5, v14
	v_add_f32_e32 v10, v10, v11
	v_add_f32_e32 v7, v8, v9
	v_add_f32_e32 v5, v5, v10
	v_add_f32_e32 v6, v6, v7
	v_add_f32_e32 v5, v5, v6
	s_waitcnt vmcnt(3)
	v_add_f32_e32 v40, v40, v41
	s_waitcnt vmcnt(2)
	v_add_f32_e32 v44, v44, v45
	s_waitcnt vmcnt(1)
	v_add_f32_e32 v48, v48, v49
	s_waitcnt vmcnt(0)
	v_add_f32_e32 v52, v52, v53
	v_add_f32_e32 v53, v54, v55
	v_add_f32_e32 v52, v52, v53
	v_add_f32_e32 v49, v50, v51
	v_add_f32_e32 v5, v5, v52
	v_add_f32_e32 v48, v48, v49
	v_add_f32_e32 v45, v46, v47
	v_add_f32_e32 v5, v5, v48
	v_add_f32_e32 v44, v44, v45
	v_add_f32_e32 v41, v42, v43
	v_add_f32_e32 v5, v5, v44
	v_add_f32_e32 v40, v40, v41
	v_add_f32_e32 v5, v5, v40
	ds_bpermute_b32 v6, v3, v5
	s_and_saveexec_b64 s[18:19], s[6:7]
	s_cbranch_execz .LBB0_482
	s_waitcnt lgkmcnt(0)
	v_add_f32_e32 v5, v5, v6
	v_fmamk_f32 v5, v5, 0x3a000000, v223
	v_mul_f32_e32 v6, 0x4b800000, v5
	v_cmp_gt_f32_e32 vcc, s56, v5
	s_nop 1
	v_cndmask_b32_e32 v5, v5, v6, vcc
	v_rsq_f32_e32 v5, v5
	s_nop 0
	v_mul_f32_e32 v6, 0x45800000, v5
	v_cndmask_b32_e32 v5, v5, v6, vcc
	ds_write_b32 v2, v5 offset:6144

.LBB0_595:
	s_or_b64 exec, exec, s[72:73]
	v_lshl_or_b32 v210, s19, 8, v238
	v_ashrrev_i32_e32 v211, 31, v210
	s_waitcnt lgkmcnt(0)
	v_lshl_add_u64 v[128:129], v[210:211], 2, v[128:129]
	global_load_dwordx4 v[184:187], v[128:129], off offset:16 nt
	global_load_dwordx4 v[188:191], v[128:129], off nt
	global_load_dwordx4 v[156:159], v[128:129], off offset:528 nt
	global_load_dwordx4 v[164:167], v[128:129], off offset:512 nt
	v_or_b32_e32 v218, 16, v212
	v_cmp_lt_i32_e32 vcc, s98, v218
	s_and_saveexec_b64 s[72:73], vcc
	s_xor_b64 s[72:73], exec, s[72:73]
	s_cbranch_execz .LBB0_600
	s_cmpk_lt_u32 s30, 0x2240
	s_mov_b64 s[76:77], -1
	s_cbranch_scc1 .LBB0_598
	s_load_dwordx2 s[74:75], s[0:1], 0x28
	s_mov_b64 s[76:77], 0

.LBB0_606:
	s_or_b64 exec, exec, s[72:73]
	v_lshl_add_u64 v[128:129], v[210:211], 2, v[128:129]
	global_load_dwordx4 v[176:179], v[128:129], off offset:16 nt
	global_load_dwordx4 v[180:183], v[128:129], off nt
	global_load_dwordx4 v[144:147], v[128:129], off offset:528 nt
	global_load_dwordx4 v[148:151], v[128:129], off offset:512 nt
	v_or_b32_e32 v216, 32, v212
	v_cmp_lt_i32_e32 vcc, s98, v216
	s_and_saveexec_b64 s[72:73], vcc
	s_xor_b64 s[72:73], exec, s[72:73]
	s_cbranch_execz .LBB0_611
	s_cmpk_lt_u32 s30, 0x2240
	s_mov_b64 s[76:77], -1
	s_cbranch_scc1 .LBB0_609
	s_load_dwordx2 s[74:75], s[0:1], 0x28
	s_mov_b64 s[76:77], 0

.LBB0_617:
	s_or_b64 exec, exec, s[72:73]
	v_lshl_add_u64 v[128:129], v[210:211], 2, v[128:129]
	global_load_dwordx4 v[168:171], v[128:129], off offset:16 nt
	global_load_dwordx4 v[172:175], v[128:129], off nt
	global_load_dwordx4 v[136:139], v[128:129], off offset:528 nt
	global_load_dwordx4 v[140:143], v[128:129], off offset:512 nt
	v_or_b32_e32 v214, 48, v212
	v_cmp_lt_i32_e32 vcc, s98, v214
	s_and_saveexec_b64 s[72:73], vcc
	s_xor_b64 s[72:73], exec, s[72:73]
	s_cbranch_execz .LBB0_622
	s_cmpk_lt_u32 s30, 0x2240
	s_mov_b64 s[76:77], -1
	s_cbranch_scc1 .LBB0_620
	s_load_dwordx2 s[74:75], s[0:1], 0x28
	s_mov_b64 s[76:77], 0

.LBB0_628:
	s_or_b64 exec, exec, s[72:73]
	v_lshl_add_u64 v[132:133], v[210:211], 2, v[128:129]
	global_load_dwordx4 v[152:155], v[132:133], off offset:16 nt
	global_load_dwordx4 v[160:163], v[132:133], off nt
	global_load_dwordx4 v[128:131], v[132:133], off offset:528 nt
	s_nop 0
	global_load_dwordx4 v[132:135], v[132:133], off offset:512 nt
	v_and_b32_e32 v213, 64, v231
	v_xor_b32_e32 v192, 16, v231
	v_add_u32_e32 v213, 64, v213
	v_cmp_lt_i32_e32 vcc, v192, v213
	s_waitcnt vmcnt(0)
	v_pk_add_f32 v[190:191], v[126:127], v[190:191]
	v_pk_add_f32 v[188:189], v[124:125], v[188:189]
	v_cndmask_b32_e32 v192, v231, v192, vcc
	v_lshlrev_b32_e32 v241, 2, v192
	v_xor_b32_e32 v192, 32, v231
	v_cmp_lt_i32_e32 vcc, v192, v213
	v_ashrrev_i32_e32 v213, 31, v212
	v_lshlrev_b64 v[220:221], 12, v[212:213]
	v_cndmask_b32_e32 v192, v231, v192, vcc
	v_lshlrev_b32_e32 v242, 2, v192
	v_lshlrev_b64 v[248:249], 8, v[212:213]
	v_mul_f32_e32 v192, v189, v189
	v_mul_f32_e32 v213, v191, v191
	v_pk_add_f32 v[184:185], v[120:121], v[184:185]
	v_fmac_f32_e32 v192, v188, v188
	v_fmac_f32_e32 v213, v190, v190
	v_add_f32_e32 v192, v192, v213
	v_mul_f32_e32 v213, v185, v185
	v_pk_add_f32 v[186:187], v[122:123], v[186:187]
	v_fmac_f32_e32 v213, v184, v184
	v_add_f32_e32 v192, v192, v213
	v_mul_f32_e32 v213, v187, v187
	v_fmac_f32_e32 v213, v186, v186
	v_add_f32_e32 v192, v213, v192
	ds_bpermute_b32 v213, v241, v192
	v_cvt_pk_bf16_f32 v244, v188, v189
	v_cvt_pk_bf16_f32 v246, v184, v185
	v_lshl_add_u64 v[184:185], s[24:25], 0, v[220:221]
	v_cvt_pk_bf16_f32 v245, v190, v191
	s_waitcnt lgkmcnt(0)
	v_add_f32_e32 v188, v192, v213
	ds_bpermute_b32 v189, v242, v188
	v_cvt_pk_bf16_f32 v247, v186, v187
	v_lshl_add_u64 v[186:187], v[210:211], 1, v[184:185]
	v_lshl_add_u64 v[184:185], s[26:27], 0, v[248:249]
	global_store_dwordx4 v[186:187], v[244:247], off
	s_and_saveexec_b64 s[72:73], s[6:7]
	s_cbranch_execz .LBB0_630
	s_lshl_b32 s74, s19, 3
	s_ashr_i32 s75, s74, 31
	s_waitcnt lgkmcnt(0)
	v_add_f32_e32 v190, v188, v189
	v_lshl_add_u64 v[188:189], s[74:75], 2, v[184:185]
	s_lshl_b32 s50, s37, 2
	v_lshl_add_u64 v[188:189], v[188:189], 0, s[50:51]
	global_store_dword v[188:189], v190, off

.LBB0_656:
	s_or_b64 exec, exec, s[72:73]
	s_waitcnt lgkmcnt(0)
	v_lshl_add_u64 v[128:129], v[210:211], 2, v[128:129]
	global_load_dwordx4 v[184:187], v[128:129], off offset:16 nt
	global_load_dwordx4 v[188:191], v[128:129], off nt
	global_load_dwordx4 v[152:155], v[128:129], off offset:528 nt
	global_load_dwordx4 v[156:159], v[128:129], off offset:512 nt
	s_movk_i32 s30, 0x1faf
	v_add_u32_e32 v218, 0x90, v212
	v_cmp_lt_i32_e32 vcc, s30, v212
	s_and_saveexec_b64 s[72:73], vcc
	s_xor_b64 s[72:73], exec, s[72:73]
	s_cbranch_execz .LBB0_662
	s_movk_i32 s30, 0x223f
	v_cmp_lt_u32_e32 vcc, s30, v218
	s_and_saveexec_b64 s[74:75], vcc
	s_xor_b64 s[74:75], exec, s[74:75]
	s_load_dwordx2 s[76:77], s[0:1], 0x28
	s_or_saveexec_b64 s[74:75], s[74:75]
	s_waitcnt lgkmcnt(0)
	v_mov_b64_e32 v[128:129], s[76:77]
	s_xor_b64 exec, exec, s[74:75]
	s_cbranch_execz .LBB0_661
	s_load_dwordx2 s[76:77], s[0:1], 0x8
	v_add_u32_e32 v192, 0xffffe050, v212
	v_lshlrev_b64 v[128:129], 13, v[192:193]
	s_waitcnt lgkmcnt(0)
	v_lshl_add_u64 v[128:129], s[76:77], 0, v[128:129]

.LBB0_668:
	s_or_b64 exec, exec, s[72:73]
	v_lshl_add_u64 v[128:129], v[210:211], 2, v[128:129]
	global_load_dwordx4 v[176:179], v[128:129], off offset:16 nt
	global_load_dwordx4 v[180:183], v[128:129], off nt
	global_load_dwordx4 v[144:147], v[128:129], off offset:528 nt
	global_load_dwordx4 v[148:151], v[128:129], off offset:512 nt
	s_movk_i32 s30, 0x1f9f
	v_add_u32_e32 v216, 0xa0, v212
	v_cmp_lt_i32_e32 vcc, s30, v212
	s_and_saveexec_b64 s[72:73], vcc
	s_xor_b64 s[72:73], exec, s[72:73]
	s_cbranch_execz .LBB0_674
	s_movk_i32 s30, 0x223f
	v_cmp_lt_u32_e32 vcc, s30, v216
	s_and_saveexec_b64 s[74:75], vcc
	s_xor_b64 s[74:75], exec, s[74:75]
	s_load_dwordx2 s[76:77], s[0:1], 0x28
	s_or_saveexec_b64 s[74:75], s[74:75]
	s_waitcnt lgkmcnt(0)
	v_mov_b64_e32 v[128:129], s[76:77]
	s_xor_b64 exec, exec, s[74:75]
	s_cbranch_execz .LBB0_673
	s_load_dwordx2 s[76:77], s[0:1], 0x8
	v_add_u32_e32 v192, 0xffffe060, v212
	v_lshlrev_b64 v[128:129], 13, v[192:193]
	s_waitcnt lgkmcnt(0)
	v_lshl_add_u64 v[128:129], s[76:77], 0, v[128:129]

.LBB0_680:
	s_or_b64 exec, exec, s[72:73]
	v_lshl_add_u64 v[128:129], v[210:211], 2, v[128:129]
	global_load_dwordx4 v[168:171], v[128:129], off offset:16 nt
	global_load_dwordx4 v[172:175], v[128:129], off nt
	global_load_dwordx4 v[136:139], v[128:129], off offset:528 nt
	global_load_dwordx4 v[140:143], v[128:129], off offset:512 nt
	s_movk_i32 s30, 0x1f8f
	v_add_u32_e32 v214, 0xb0, v212
	v_cmp_lt_i32_e32 vcc, s30, v212
	s_and_saveexec_b64 s[72:73], vcc
	s_xor_b64 s[72:73], exec, s[72:73]
	s_cbranch_execz .LBB0_686
	s_movk_i32 s30, 0x223f
	v_cmp_lt_u32_e32 vcc, s30, v214
	s_and_saveexec_b64 s[74:75], vcc
	s_xor_b64 s[74:75], exec, s[74:75]
	s_load_dwordx2 s[76:77], s[0:1], 0x28
	s_or_saveexec_b64 s[74:75], s[74:75]
	s_waitcnt lgkmcnt(0)
	v_mov_b64_e32 v[128:129], s[76:77]
	s_xor_b64 exec, exec, s[74:75]
	s_cbranch_execz .LBB0_685
	s_load_dwordx2 s[76:77], s[0:1], 0x8
	v_add_u32_e32 v192, 0xffffe070, v212
	v_lshlrev_b64 v[128:129], 13, v[192:193]
	s_waitcnt lgkmcnt(0)
	v_lshl_add_u64 v[128:129], s[76:77], 0, v[128:129]

.LBB0_692:
	s_or_b64 exec, exec, s[72:73]
	v_lshl_add_u64 v[132:133], v[210:211], 2, v[128:129]
	global_load_dwordx4 v[160:163], v[132:133], off offset:16 nt
	global_load_dwordx4 v[164:167], v[132:133], off nt
	global_load_dwordx4 v[128:131], v[132:133], off offset:528 nt
	s_nop 0
	global_load_dwordx4 v[132:135], v[132:133], off offset:512 nt
	s_waitcnt vmcnt(14)
	v_pk_add_f32 v[190:191], v[62:63], v[190:191]
	v_pk_add_f32 v[188:189], v[60:61], v[188:189]
	v_mul_f32_e32 v215, v191, v191
	v_mul_f32_e32 v192, v189, v189
	v_pk_add_f32 v[184:185], v[56:57], v[184:185]
	v_fmac_f32_e32 v192, v188, v188
	v_fmac_f32_e32 v215, v190, v190
	v_add_f32_e32 v192, v192, v215
	v_mul_f32_e32 v215, v185, v185
	v_pk_add_f32 v[186:187], v[58:59], v[186:187]
	v_fmac_f32_e32 v215, v184, v184
	v_add_f32_e32 v192, v192, v215
	v_mul_f32_e32 v215, v187, v187
	v_fmac_f32_e32 v215, v186, v186
	v_add_f32_e32 v192, v215, v192
	ds_bpermute_b32 v215, v241, v192
	v_cvt_pk_bf16_f32 v244, v188, v189
	v_ashrrev_i32_e32 v221, 31, v220
	v_lshlrev_b64 v[212:213], 12, v[220:221]
	v_lshlrev_b64 v[220:221], 8, v[220:221]
	s_waitcnt lgkmcnt(0)
	v_add_f32_e32 v188, v192, v215
	ds_bpermute_b32 v189, v242, v188
	v_cvt_pk_bf16_f32 v246, v184, v185
	v_lshl_add_u64 v[184:185], s[24:25], 0, v[212:213]
	v_cvt_pk_bf16_f32 v245, v190, v191
	v_cvt_pk_bf16_f32 v247, v186, v187
	v_lshl_add_u64 v[186:187], v[210:211], 1, v[184:185]
	v_lshl_add_u64 v[184:185], s[26:27], 0, v[220:221]
	global_store_dwordx4 v[186:187], v[244:247], off
	s_and_saveexec_b64 s[72:73], s[6:7]
	s_cbranch_execz .LBB0_694
	s_lshl_b32 s74, s19, 3
	s_ashr_i32 s75, s74, 31
	s_waitcnt lgkmcnt(0)
	v_add_f32_e32 v190, v188, v189
	v_lshl_add_u64 v[188:189], s[74:75], 2, v[184:185]
	s_lshl_b32 s50, s37, 2
	v_lshl_add_u64 v[188:189], v[188:189], 0, s[50:51]
	global_store_dword v[188:189], v190, off
